# v032 + final y stores write-through and non-temporal (sc1 nt): nothing left for the end-of-kernel cache writeback
# speedup vs baseline: 1.0033x; 1.0033x over previous
;     __device__ __forceinline__ void operator()(f32x4 (&acc)[2][2][4][2], const pg8::Unit& u, int wr, int wc, int fr, int fq) const {
;     ...
;         f32x4 gg[2][2];
; #pragma unroll
;         for (int bj = 0; bj < 2; ++bj)
; #pragma unroll
;             for (int n = 0; n < 2; ++n) gg[bj][n] = *(const f32x4*)(fng + col0 + bj * 128 + n * 16);
; #pragma unroll
;         for (int ai = 0; ai < 2; ++ai)
; #pragma unroll
;             for (int m = 0; m < 4; ++m) {
;                 const int row = row0 + ai * 128 + m * 16;
;                 const f32x4 pa = *(const f32x4*)(ss + (size_t)row * 32 + 8 * fq), pb = *(const f32x4*)(ss + (size_t)row * 32 + 8 * fq + 4);
;                 float sq = ((pa[0] + pa[1]) + (pa[2] + pa[3])) + ((pb[0] + pb[1]) + (pb[2] + pb[3]));
;                 sq += __shfl_xor(sq, 16); sq += __shfl_xor(sq, 32);
;                 const float rinv = __builtin_amdgcn_rsqf(sq * (1.0f / DM) + 1e-6f);
;                 float* orow = oy + (size_t)row * DM + col0;
; #pragma unroll
;                 for (int bj = 0; bj < 2; ++bj)
; #pragma unroll
;                     for (int n = 0; n < 2; ++n) __builtin_nontemporal_store(acc[ai][bj][m][n] * rinv * gg[bj][n], (f32x4*)(orow + bj * 128 + n * 16));
.LBB0_904:
	s_or_b64 exec, exec, s[36:37]
	s_barrier
	v_lshl_add_u64 v[130:131], v[148:149], 0, v[130:131]
	global_load_dwordx4 v[188:191], v[130:131], off
	global_load_dwordx4 v[196:199], v[130:131], off offset:16
	v_readlane_b32 s64, v234, 3
	v_readlane_b32 s74, v234, 13
	v_readlane_b32 s75, v234, 14
	v_lshl_add_u64 v[166:167], v[148:149], 0, v[166:167]
	v_lshl_add_u64 v[170:171], v[148:149], 0, v[170:171]
	v_lshl_add_u64 v[128:129], v[128:129], 2, s[74:75]
	global_load_dwordx4 v[140:143], v[128:129], off
	global_load_dwordx4 v[136:139], v[128:129], off offset:64
	s_waitcnt lgkmcnt(0)
	global_load_dwordx4 v[132:135], v[128:129], off offset:512
	s_nop 0
	global_load_dwordx4 v[128:131], v[128:129], off offset:576
	v_lshl_add_u64 v[174:175], v[148:149], 0, v[174:175]
	s_andn2_b64 vcc, exec, s[34:35]
	v_readlane_b32 s65, v234, 4
	v_readlane_b32 s66, v234, 5
	v_readlane_b32 s67, v234, 6
	v_readlane_b32 s68, v234, 7
	v_readlane_b32 s69, v234, 8
	v_readlane_b32 s70, v234, 9
	v_readlane_b32 s71, v234, 10
	v_readlane_b32 s72, v234, 11
	v_readlane_b32 s73, v234, 12
	v_readlane_b32 s76, v234, 15
	v_readlane_b32 s77, v234, 16
	v_readlane_b32 s78, v234, 17
	v_readlane_b32 s79, v234, 18
	s_waitcnt vmcnt(5)
	v_mov_b32_e32 v192, v188
	s_waitcnt vmcnt(4)
	v_mov_b32_e32 v193, v196
	v_mov_b32_e32 v196, v189
	v_mov_b32_e32 v188, v190
	v_mov_b32_e32 v189, v198
	v_mov_b32_e32 v198, v191
	v_pk_add_f32 v[190:191], v[192:193], v[196:197]
	v_pk_add_f32 v[188:189], v[188:189], v[198:199]
	s_nop 0
	v_pk_add_f32 v[188:189], v[190:191], v[188:189]
	s_nop 0
	v_add_f32_e32 v187, v188, v189
	ds_bpermute_b32 v188, v185, v187
	s_waitcnt lgkmcnt(0)
	v_add_f32_e32 v187, v187, v188
	ds_bpermute_b32 v188, v186, v187
	s_waitcnt lgkmcnt(0)
	v_add_f32_e32 v187, v187, v188
	v_fmamk_f32 v187, v187, 0x3a000000, v184
	v_rsq_f32_e32 v188, v187
	s_nop 0
	v_pk_mul_f32 v[192:193], v[124:125], v[188:189] op_sel_hi:[1,0]
	v_pk_mul_f32 v[190:191], v[126:127], v[188:189] op_sel_hi:[1,0]
	v_pk_mul_f32 v[196:197], v[120:121], v[188:189] op_sel_hi:[1,0]
	v_pk_mul_f32 v[198:199], v[122:123], v[188:189] op_sel_hi:[1,0]
	v_pk_mul_f32 v[200:201], v[92:93], v[188:189] op_sel_hi:[1,0]
	v_pk_mul_f32 v[202:203], v[94:95], v[188:189] op_sel_hi:[1,0]
	v_pk_mul_f32 v[204:205], v[88:89], v[188:189] op_sel_hi:[1,0]
	v_pk_mul_f32 v[206:207], v[90:91], v[188:189] op_sel_hi:[1,0]
	s_waitcnt vmcnt(3)
	v_pk_mul_f32 v[190:191], v[142:143], v[190:191]
	v_pk_mul_f32 v[188:189], v[140:141], v[192:193]
	s_waitcnt vmcnt(2)
	v_pk_mul_f32 v[198:199], v[138:139], v[198:199]
	v_pk_mul_f32 v[196:197], v[136:137], v[196:197]
	s_waitcnt vmcnt(1)
	v_pk_mul_f32 v[202:203], v[134:135], v[202:203]
	v_pk_mul_f32 v[200:201], v[132:133], v[200:201]
	s_waitcnt vmcnt(0)
	v_pk_mul_f32 v[206:207], v[130:131], v[206:207]
	v_pk_mul_f32 v[204:205], v[128:129], v[204:205]
	global_store_dwordx4 v[150:151], v[188:191], off sc1 nt
	global_store_dwordx4 v[150:151], v[196:199], off offset:64 sc1 nt
	global_store_dwordx4 v[150:151], v[200:203], off offset:512 sc1 nt
	global_store_dwordx4 v[150:151], v[204:207], off offset:576 sc1 nt
	global_load_dwordx4 v[188:191], v[166:167], off
	s_nop 0
	global_load_dwordx4 v[196:199], v[166:167], off offset:16
	v_lshl_add_u64 v[192:193], v[148:149], 0, v[168:169]
	s_waitcnt vmcnt(1)
	v_mov_b32_e32 v150, v188
	s_waitcnt vmcnt(0)
	v_mov_b32_e32 v151, v196
	v_mov_b32_e32 v196, v189
	v_mov_b32_e32 v166, v190
	v_mov_b32_e32 v167, v198
	v_mov_b32_e32 v198, v191
	v_pk_add_f32 v[150:151], v[150:151], v[196:197]
	v_pk_add_f32 v[166:167], v[166:167], v[198:199]
	s_nop 0
	v_pk_add_f32 v[150:151], v[150:151], v[166:167]
	s_nop 0
	v_add_f32_e32 v150, v150, v151
	ds_bpermute_b32 v151, v185, v150
	s_waitcnt lgkmcnt(0)
	v_add_f32_e32 v150, v150, v151
	ds_bpermute_b32 v151, v186, v150
	s_waitcnt lgkmcnt(0)
	v_add_f32_e32 v150, v150, v151
	v_fmamk_f32 v150, v150, 0x3a000000, v184
	v_rsq_f32_e32 v150, v150
	s_nop 0
	v_pk_mul_f32 v[166:167], v[116:117], v[150:151] op_sel_hi:[1,0]
	v_pk_mul_f32 v[168:169], v[118:119], v[150:151] op_sel_hi:[1,0]
	v_pk_mul_f32 v[188:189], v[112:113], v[150:151] op_sel_hi:[1,0]
	v_pk_mul_f32 v[190:191], v[114:115], v[150:151] op_sel_hi:[1,0]
	v_pk_mul_f32 v[196:197], v[84:85], v[150:151] op_sel_hi:[1,0]
	v_pk_mul_f32 v[198:199], v[86:87], v[150:151] op_sel_hi:[1,0]
	v_pk_mul_f32 v[200:201], v[80:81], v[150:151] op_sel_hi:[1,0]
	v_pk_mul_f32 v[150:151], v[82:83], v[150:151] op_sel_hi:[1,0]
	v_pk_mul_f32 v[168:169], v[142:143], v[168:169]
	v_pk_mul_f32 v[166:167], v[140:141], v[166:167]
	v_pk_mul_f32 v[190:191], v[138:139], v[190:191]
	v_pk_mul_f32 v[188:189], v[136:137], v[188:189]
	v_pk_mul_f32 v[198:199], v[134:135], v[198:199]
	v_pk_mul_f32 v[196:197], v[132:133], v[196:197]
	v_pk_mul_f32 v[202:203], v[130:131], v[150:151]
	v_pk_mul_f32 v[200:201], v[128:129], v[200:201]
	global_store_dwordx4 v[152:153], v[166:169], off sc1 nt
	global_store_dwordx4 v[152:153], v[188:191], off offset:64 sc1 nt
	global_store_dwordx4 v[152:153], v[196:199], off offset:512 sc1 nt
	global_store_dwordx4 v[152:153], v[200:203], off offset:576 sc1 nt
	global_load_dwordx4 v[150:153], v[192:193], off
	s_nop 0
	global_load_dwordx4 v[166:169], v[192:193], off offset:16
	s_waitcnt vmcnt(1)
	v_mov_b32_e32 v188, v150
	s_waitcnt vmcnt(0)
	v_mov_b32_e32 v189, v166
	v_mov_b32_e32 v166, v151
	v_mov_b32_e32 v150, v152
	v_mov_b32_e32 v151, v168
	v_mov_b32_e32 v168, v153
	v_pk_add_f32 v[152:153], v[188:189], v[166:167]
	v_pk_add_f32 v[150:151], v[150:151], v[168:169]
	s_nop 0
	v_pk_add_f32 v[150:151], v[152:153], v[150:151]
	s_nop 0
	v_add_f32_e32 v150, v150, v151
	ds_bpermute_b32 v151, v185, v150
	s_waitcnt lgkmcnt(0)
;     __device__ __forceinline__ void operator()(f32x4 (&acc)[2][2][4][2], const pg8::Unit& u, int wr, int wc, int fr, int fq) const {
;     ...
;             for (int m = 0; m < 4; ++m) {
;                 const int row = row0 + ai * 128 + m * 16;
;                 const f32x4 pa = *(const f32x4*)(ss + (size_t)row * 32 + 8 * fq), pb = *(const f32x4*)(ss + (size_t)row * 32 + 8 * fq + 4);
;                 float sq = ((pa[0] + pa[1]) + (pa[2] + pa[3])) + ((pb[0] + pb[1]) + (pb[2] + pb[3]));
;                 sq += __shfl_xor(sq, 16); sq += __shfl_xor(sq, 32);
;                 const float rinv = __builtin_amdgcn_rsqf(sq * (1.0f / DM) + 1e-6f);
;                 float* orow = oy + (size_t)row * DM + col0;
; #pragma unroll
;                 for (int bj = 0; bj < 2; ++bj)
; #pragma unroll
;                     for (int n = 0; n < 2; ++n) __builtin_nontemporal_store(acc[ai][bj][m][n] * rinv * gg[bj][n], (f32x4*)(orow + bj * 128 + n * 16));
	v_add_f32_e32 v150, v150, v151
	ds_bpermute_b32 v151, v186, v150
	s_waitcnt lgkmcnt(0)
	v_add_f32_e32 v150, v150, v151
	v_fmamk_f32 v150, v150, 0x3a000000, v184
	v_rsq_f32_e32 v150, v150
	s_nop 0
	v_pk_mul_f32 v[166:167], v[108:109], v[150:151] op_sel_hi:[1,0]
	v_pk_mul_f32 v[152:153], v[110:111], v[150:151] op_sel_hi:[1,0]
	v_pk_mul_f32 v[188:189], v[104:105], v[150:151] op_sel_hi:[1,0]
	v_pk_mul_f32 v[168:169], v[106:107], v[150:151] op_sel_hi:[1,0]
	v_pk_mul_f32 v[192:193], v[76:77], v[150:151] op_sel_hi:[1,0]
	v_pk_mul_f32 v[190:191], v[78:79], v[150:151] op_sel_hi:[1,0]
	v_pk_mul_f32 v[196:197], v[72:73], v[150:151] op_sel_hi:[1,0]
	v_pk_mul_f32 v[198:199], v[74:75], v[150:151] op_sel_hi:[1,0]
	v_pk_mul_f32 v[152:153], v[142:143], v[152:153]
	v_pk_mul_f32 v[150:151], v[140:141], v[166:167]
	v_pk_mul_f32 v[168:169], v[138:139], v[168:169]
	v_pk_mul_f32 v[166:167], v[136:137], v[188:189]
	v_pk_mul_f32 v[190:191], v[134:135], v[190:191]
	v_pk_mul_f32 v[188:189], v[132:133], v[192:193]
	v_pk_mul_f32 v[198:199], v[130:131], v[198:199]
	v_pk_mul_f32 v[196:197], v[128:129], v[196:197]
	global_store_dwordx4 v[154:155], v[150:153], off sc1 nt
	global_store_dwordx4 v[154:155], v[166:169], off offset:64 sc1 nt
	global_store_dwordx4 v[154:155], v[188:191], off offset:512 sc1 nt
	global_store_dwordx4 v[154:155], v[196:199], off offset:576 sc1 nt
	global_load_dwordx4 v[150:153], v[170:171], off
	s_nop 0
	global_load_dwordx4 v[166:169], v[170:171], off offset:16
	s_waitcnt vmcnt(1)
	v_mov_b32_e32 v154, v150
	s_waitcnt vmcnt(0)
	v_mov_b32_e32 v155, v166
	v_mov_b32_e32 v166, v151
	v_mov_b32_e32 v150, v152
	v_mov_b32_e32 v151, v168
	v_mov_b32_e32 v168, v153
	v_pk_add_f32 v[152:153], v[154:155], v[166:167]
	v_pk_add_f32 v[150:151], v[150:151], v[168:169]
	v_lshl_add_u64 v[154:155], v[148:149], 0, v[172:173]
	v_pk_add_f32 v[150:151], v[152:153], v[150:151]
	s_nop 0
	v_add_f32_e32 v150, v150, v151
	ds_bpermute_b32 v151, v185, v150
	s_waitcnt lgkmcnt(0)
	v_add_f32_e32 v150, v150, v151
	ds_bpermute_b32 v151, v186, v150
	s_waitcnt lgkmcnt(0)
	v_add_f32_e32 v150, v150, v151
	v_fmamk_f32 v150, v150, 0x3a000000, v184
	v_rsq_f32_e32 v150, v150
	s_nop 0
	v_pk_mul_f32 v[166:167], v[100:101], v[150:151] op_sel_hi:[1,0]
	v_pk_mul_f32 v[152:153], v[102:103], v[150:151] op_sel_hi:[1,0]
	v_pk_mul_f32 v[170:171], v[96:97], v[150:151] op_sel_hi:[1,0]
	v_pk_mul_f32 v[168:169], v[98:99], v[150:151] op_sel_hi:[1,0]
	v_pk_mul_f32 v[188:189], v[68:69], v[150:151] op_sel_hi:[1,0]
	v_pk_mul_f32 v[172:173], v[70:71], v[150:151] op_sel_hi:[1,0]
	v_pk_mul_f32 v[192:193], v[64:65], v[150:151] op_sel_hi:[1,0]
	v_pk_mul_f32 v[190:191], v[66:67], v[150:151] op_sel_hi:[1,0]
	v_pk_mul_f32 v[152:153], v[142:143], v[152:153]
	v_pk_mul_f32 v[150:151], v[140:141], v[166:167]
	v_pk_mul_f32 v[168:169], v[138:139], v[168:169]
	v_pk_mul_f32 v[166:167], v[136:137], v[170:171]
	v_pk_mul_f32 v[172:173], v[134:135], v[172:173]
	v_pk_mul_f32 v[170:171], v[132:133], v[188:189]
	v_pk_mul_f32 v[190:191], v[130:131], v[190:191]
	v_pk_mul_f32 v[188:189], v[128:129], v[192:193]
	global_store_dwordx4 v[156:157], v[150:153], off sc1 nt
	global_store_dwordx4 v[156:157], v[166:169], off offset:64 sc1 nt
	global_store_dwordx4 v[156:157], v[170:173], off offset:512 sc1 nt
	global_store_dwordx4 v[156:157], v[188:191], off offset:576 sc1 nt
	global_load_dwordx4 v[150:153], v[154:155], off
	s_nop 0
	global_load_dwordx4 v[154:157], v[154:155], off offset:16
	s_waitcnt vmcnt(1)
	v_mov_b32_e32 v166, v150
	s_waitcnt vmcnt(0)
	v_mov_b32_e32 v167, v154
	v_mov_b32_e32 v154, v151
	v_mov_b32_e32 v150, v152
	v_mov_b32_e32 v151, v156
	v_mov_b32_e32 v156, v153
	v_pk_add_f32 v[152:153], v[166:167], v[154:155]
	v_pk_add_f32 v[150:151], v[150:151], v[156:157]
	s_nop 0
	v_pk_add_f32 v[150:151], v[152:153], v[150:151]
	s_nop 0
	v_add_f32_e32 v150, v150, v151
	ds_bpermute_b32 v151, v185, v150
	s_waitcnt lgkmcnt(0)
	v_add_f32_e32 v150, v150, v151
	ds_bpermute_b32 v151, v186, v150
	s_waitcnt lgkmcnt(0)
	v_add_f32_e32 v150, v150, v151
	v_fmamk_f32 v150, v150, 0x3a000000, v184
	v_rsq_f32_e32 v150, v150
	s_nop 0
	v_pk_mul_f32 v[154:155], v[60:61], v[150:151] op_sel_hi:[1,0]
	v_pk_mul_f32 v[152:153], v[62:63], v[150:151] op_sel_hi:[1,0]
	v_pk_mul_f32 v[166:167], v[56:57], v[150:151] op_sel_hi:[1,0]
	v_pk_mul_f32 v[156:157], v[58:59], v[150:151] op_sel_hi:[1,0]
	v_pk_mul_f32 v[170:171], v[28:29], v[150:151] op_sel_hi:[1,0]
	v_pk_mul_f32 v[168:169], v[30:31], v[150:151] op_sel_hi:[1,0]
	v_pk_mul_f32 v[188:189], v[24:25], v[150:151] op_sel_hi:[1,0]
	v_pk_mul_f32 v[172:173], v[26:27], v[150:151] op_sel_hi:[1,0]
	v_pk_mul_f32 v[152:153], v[142:143], v[152:153]
	v_pk_mul_f32 v[150:151], v[140:141], v[154:155]
	v_pk_mul_f32 v[156:157], v[138:139], v[156:157]
	v_pk_mul_f32 v[154:155], v[136:137], v[166:167]
	v_pk_mul_f32 v[168:169], v[134:135], v[168:169]
	v_pk_mul_f32 v[166:167], v[132:133], v[170:171]
	v_pk_mul_f32 v[172:173], v[130:131], v[172:173]
	v_pk_mul_f32 v[170:171], v[128:129], v[188:189]
	global_store_dwordx4 v[158:159], v[150:153], off sc1 nt
	global_store_dwordx4 v[158:159], v[154:157], off offset:64 sc1 nt
	global_store_dwordx4 v[158:159], v[166:169], off offset:512 sc1 nt
	global_store_dwordx4 v[158:159], v[170:173], off offset:576 sc1 nt
	global_load_dwordx4 v[150:153], v[174:175], off
	s_nop 0
	global_load_dwordx4 v[154:157], v[174:175], off offset:16
	s_waitcnt vmcnt(1)
	v_mov_b32_e32 v158, v150
	s_waitcnt vmcnt(0)
; #define PG8_BAR __builtin_amdgcn_s_barrier()
; template <class Epi, class Sched, bool ALIGN_EPI = true>
; __device__ __forceinline__ void gemm_phase(LAS unsigned char* lds, const Gemm g, const Sched& S, const Epi& E) {
;     ...
;         if constexpr (ALIGN_EPI) { if (wr == 0) PG8_BAR; }
;         E(acc, cur, wr, wc, fr, fq); if (Sched::PUBLISH) pend = cur.pm;
;         if (!has_next) break;
; #pragma unroll
;         for (int a = 0; a < 2; ++a)
; #pragma unroll
;             for (int b = 0; b < 2; ++b)
; #pragma unroll
;                 for (int m = 0; m < 4; ++m)
; #pragma unroll
;                     for (int n = 0; n < 2; ++n) acc[a][b][m][n] = (f32x4){0.f, 0.f, 0.f, 0.f};
;         cur = nxt; cA = nA; cB = nB; ++ui;
;         if constexpr (ALIGN_EPI) { if (wr == 1) PG8_BAR; }
;     __device__ __forceinline__ void operator()(f32x4 (&acc)[2][2][4][2], const pg8::Unit& u, int wr, int wc, int fr, int fq) const {
;     ...
;             for (int m = 0; m < 4; ++m) {
;                 const int row = row0 + ai * 128 + m * 16;
;                 const f32x4 pa = *(const f32x4*)(ss + (size_t)row * 32 + 8 * fq), pb = *(const f32x4*)(ss + (size_t)row * 32 + 8 * fq + 4);
;                 float sq = ((pa[0] + pa[1]) + (pa[2] + pa[3])) + ((pb[0] + pb[1]) + (pb[2] + pb[3]));
;                 sq += __shfl_xor(sq, 16); sq += __shfl_xor(sq, 32);
;                 const float rinv = __builtin_amdgcn_rsqf(sq * (1.0f / DM) + 1e-6f);
;                 float* orow = oy + (size_t)row * DM + col0;
; #pragma unroll
;                 for (int bj = 0; bj < 2; ++bj)
; #pragma unroll
;                     for (int n = 0; n < 2; ++n) __builtin_nontemporal_store(acc[ai][bj][m][n] * rinv * gg[bj][n], (f32x4*)(orow + bj * 128 + n * 16));
	v_mov_b32_e32 v159, v154
	v_mov_b32_e32 v154, v151
	v_mov_b32_e32 v150, v152
	v_mov_b32_e32 v151, v156
	v_mov_b32_e32 v156, v153
	v_pk_add_f32 v[152:153], v[158:159], v[154:155]
	v_pk_add_f32 v[150:151], v[150:151], v[156:157]
	v_lshl_add_u64 v[158:159], v[148:149], 0, v[176:177]
	v_pk_add_f32 v[150:151], v[152:153], v[150:151]
	s_nop 0
	v_add_f32_e32 v150, v150, v151
	ds_bpermute_b32 v151, v185, v150
	s_waitcnt lgkmcnt(0)
	v_add_f32_e32 v150, v150, v151
	ds_bpermute_b32 v151, v186, v150
	s_waitcnt lgkmcnt(0)
	v_add_f32_e32 v150, v150, v151
	v_fmamk_f32 v150, v150, 0x3a000000, v184
	v_rsq_f32_e32 v150, v150
	s_nop 0
	v_pk_mul_f32 v[154:155], v[52:53], v[150:151] op_sel_hi:[1,0]
	v_pk_mul_f32 v[152:153], v[54:55], v[150:151] op_sel_hi:[1,0]
	v_pk_mul_f32 v[166:167], v[48:49], v[150:151] op_sel_hi:[1,0]
	v_pk_mul_f32 v[156:157], v[50:51], v[150:151] op_sel_hi:[1,0]
	v_pk_mul_f32 v[170:171], v[20:21], v[150:151] op_sel_hi:[1,0]
	v_pk_mul_f32 v[168:169], v[22:23], v[150:151] op_sel_hi:[1,0]
	v_pk_mul_f32 v[174:175], v[16:17], v[150:151] op_sel_hi:[1,0]
	v_pk_mul_f32 v[172:173], v[18:19], v[150:151] op_sel_hi:[1,0]
	v_pk_mul_f32 v[152:153], v[142:143], v[152:153]
	v_pk_mul_f32 v[150:151], v[140:141], v[154:155]
	v_pk_mul_f32 v[156:157], v[138:139], v[156:157]
	v_pk_mul_f32 v[154:155], v[136:137], v[166:167]
	v_pk_mul_f32 v[168:169], v[134:135], v[168:169]
	v_pk_mul_f32 v[166:167], v[132:133], v[170:171]
	v_pk_mul_f32 v[172:173], v[130:131], v[172:173]
	v_pk_mul_f32 v[170:171], v[128:129], v[174:175]
	global_store_dwordx4 v[160:161], v[150:153], off sc1 nt
	global_store_dwordx4 v[160:161], v[154:157], off offset:64 sc1 nt
	global_store_dwordx4 v[160:161], v[166:169], off offset:512 sc1 nt
	global_store_dwordx4 v[160:161], v[170:173], off offset:576 sc1 nt
	global_load_dwordx4 v[150:153], v[158:159], off
	s_nop 0
	global_load_dwordx4 v[154:157], v[158:159], off offset:16
	v_lshl_add_u64 v[170:171], v[148:149], 0, v[178:179]
	s_waitcnt vmcnt(1)
	v_mov_b32_e32 v158, v150
	s_waitcnt vmcnt(0)
	v_mov_b32_e32 v159, v154
	v_mov_b32_e32 v154, v151
	v_mov_b32_e32 v150, v152
	v_mov_b32_e32 v151, v156
	v_mov_b32_e32 v156, v153
	v_pk_add_f32 v[152:153], v[158:159], v[154:155]
	v_pk_add_f32 v[150:151], v[150:151], v[156:157]
	s_nop 0
	v_pk_add_f32 v[150:151], v[152:153], v[150:151]
	s_nop 0
	v_add_f32_e32 v150, v150, v151
	ds_bpermute_b32 v151, v185, v150
	s_waitcnt lgkmcnt(0)
	v_add_f32_e32 v150, v150, v151
	ds_bpermute_b32 v151, v186, v150
	s_waitcnt lgkmcnt(0)
	v_add_f32_e32 v150, v150, v151
	v_fmamk_f32 v150, v150, 0x3a000000, v184
	v_rsq_f32_e32 v150, v150
	s_nop 0
	v_pk_mul_f32 v[154:155], v[44:45], v[150:151] op_sel_hi:[1,0]
	v_pk_mul_f32 v[152:153], v[46:47], v[150:151] op_sel_hi:[1,0]
	v_pk_mul_f32 v[158:159], v[40:41], v[150:151] op_sel_hi:[1,0]
	v_pk_mul_f32 v[156:157], v[42:43], v[150:151] op_sel_hi:[1,0]
	v_pk_mul_f32 v[166:167], v[12:13], v[150:151] op_sel_hi:[1,0]
	v_pk_mul_f32 v[160:161], v[14:15], v[150:151] op_sel_hi:[1,0]
	v_pk_mul_f32 v[172:173], v[8:9], v[150:151] op_sel_hi:[1,0]
	v_pk_mul_f32 v[168:169], v[10:11], v[150:151] op_sel_hi:[1,0]
	v_pk_mul_f32 v[152:153], v[142:143], v[152:153]
	v_pk_mul_f32 v[150:151], v[140:141], v[154:155]
	v_pk_mul_f32 v[156:157], v[138:139], v[156:157]
	v_pk_mul_f32 v[154:155], v[136:137], v[158:159]
	v_pk_mul_f32 v[160:161], v[134:135], v[160:161]
	v_pk_mul_f32 v[158:159], v[132:133], v[166:167]
	v_pk_mul_f32 v[168:169], v[130:131], v[168:169]
	v_pk_mul_f32 v[166:167], v[128:129], v[172:173]
	global_store_dwordx4 v[162:163], v[150:153], off sc1 nt
	global_store_dwordx4 v[162:163], v[154:157], off offset:64 sc1 nt
	global_store_dwordx4 v[162:163], v[158:161], off offset:512 sc1 nt
	global_store_dwordx4 v[162:163], v[166:169], off offset:576 sc1 nt
	global_load_dwordx4 v[150:153], v[170:171], off
	s_nop 0
	global_load_dwordx4 v[154:157], v[170:171], off offset:16
	s_waitcnt vmcnt(1)
	v_mov_b32_e32 v158, v150
	s_waitcnt vmcnt(0)
	v_mov_b32_e32 v159, v154
	v_mov_b32_e32 v154, v151
	v_mov_b32_e32 v150, v152
	v_mov_b32_e32 v151, v156
	v_mov_b32_e32 v156, v153
	v_pk_add_f32 v[152:153], v[158:159], v[154:155]
	v_pk_add_f32 v[150:151], v[150:151], v[156:157]
	s_nop 0
	v_pk_add_f32 v[150:151], v[152:153], v[150:151]
	s_nop 0
	v_add_f32_e32 v150, v150, v151
	ds_bpermute_b32 v151, v185, v150
	s_waitcnt lgkmcnt(0)
	v_add_f32_e32 v150, v150, v151
	ds_bpermute_b32 v151, v186, v150
	s_waitcnt lgkmcnt(0)
	v_add_f32_e32 v150, v150, v151
	v_fmamk_f32 v150, v150, 0x3a000000, v184
	v_rsq_f32_e32 v150, v150
	s_nop 0
	v_pk_mul_f32 v[152:153], v[36:37], v[150:151] op_sel_hi:[1,0]
	v_pk_mul_f32 v[154:155], v[38:39], v[150:151] op_sel_hi:[1,0]
	v_pk_mul_f32 v[156:157], v[32:33], v[150:151] op_sel_hi:[1,0]
	v_pk_mul_f32 v[158:159], v[34:35], v[150:151] op_sel_hi:[1,0]
	v_pk_mul_f32 v[160:161], v[4:5], v[150:151] op_sel_hi:[1,0]
	v_pk_mul_f32 v[162:163], v[6:7], v[150:151] op_sel_hi:[1,0]
	v_pk_mul_f32 v[166:167], v[0:1], v[150:151] op_sel_hi:[1,0]
	v_pk_mul_f32 v[150:151], v[2:3], v[150:151] op_sel_hi:[1,0]
	v_pk_mul_f32 v[142:143], v[142:143], v[154:155]
	v_pk_mul_f32 v[140:141], v[140:141], v[152:153]
	v_pk_mul_f32 v[138:139], v[138:139], v[158:159]
	v_pk_mul_f32 v[136:137], v[136:137], v[156:157]
	v_pk_mul_f32 v[134:135], v[134:135], v[162:163]
	v_pk_mul_f32 v[132:133], v[132:133], v[160:161]
	v_pk_mul_f32 v[130:131], v[130:131], v[150:151]
	v_pk_mul_f32 v[128:129], v[128:129], v[166:167]
	global_store_dwordx4 v[164:165], v[140:143], off sc1 nt
	global_store_dwordx4 v[164:165], v[136:139], off offset:64 sc1 nt
	global_store_dwordx4 v[164:165], v[132:135], off offset:512 sc1 nt
	global_store_dwordx4 v[164:165], v[128:131], off offset:576 sc1 nt
	s_cbranch_vccnz .LBB0_848
	s_andn2_b64 vcc, exec, s[18:19]
	s_cbranch_vccnz .LBB0_847
	s_barrier
	s_branch .LBB0_847
